# HID hidden activations also stored as contiguous 1KiB 16x32 fragments: P8 epilogue stores and P9 A-operand LDS-DMA loads become contiguous (on top of the X16 fragment layout)
# speedup vs baseline: 1.0068x; 1.0048x over previous
; #define PG8_LAS __attribute__((address_space(3)))
; __device__ __forceinline__ unsigned cvt_pk_bf16(float lo, float hi) { unsigned r; asm volatile("v_cvt_pk_bf16_f32 %0, %1, %2" : "=v"(r) : "v"(lo), "v"(hi)); return r; }
; __device__ __forceinline__ f32x2 swiglu_pk(f32x2 g, f32x2 u) {
;     const f32x2 t = g * (-LOG2E); f32x2 e; e.x = __builtin_amdgcn_exp2f(t.x); e.y = __builtin_amdgcn_exp2f(t.y);
;     const f32x2 d = e + 1.0f; f32x2 r; r.x = __builtin_amdgcn_rcpf(d.x); r.y = __builtin_amdgcn_rcpf(d.y);
;     return (g * r) * u;
; }
;     __device__ __forceinline__ void operator()(const f32x4 (&acc)[2][2][4][2], const Unit& u, int wr, int wc, int fr, int fq, int par, PG8_LAS unsigned char* lds) const {
;         const int row0 = u.pm * BM + wr * 64 + fr, col0 = u.pn * HALF + wc * 32 + 8 * fq;
;         const PG8_LAS float* rp = (const PG8_LAS float*)(lds + STAGE_BYTES + 5120) + par * 512;
;         const PG8_LAS float* sp = rp + 256 + wc * 32 + 8 * fq;
;         const f32x4 sg0 = *(const PG8_LAS f32x4*)sp, sg1 = *(const PG8_LAS f32x4*)(sp + 4), su0 = *(const PG8_LAS f32x4*)(sp + HALF), su1 = *(const PG8_LAS f32x4*)(sp + HALF + 4);
;         float rsv[8];
; #pragma unroll
;         for (int i = 0; i < 8; ++i) rsv[i] = rp[(i >> 2) * HALF + wr * 64 + (i & 3) * 16 + fr];
; #pragma unroll
;         for (int ai = 0; ai < 2; ++ai)
; #pragma unroll
;             for (int m = 0; m < 4; ++m) {
;                 const int row = row0 + ai * HALF + m * 16;
;                 const float rs = rsv[ai * 4 + m];
;                 const f32x4 g0 = acc[ai][0][m][0] * rs + sg0, g1 = acc[ai][0][m][1] * rs + sg1, u0 = acc[ai][1][m][0] * rs + su0, u1 = acc[ai][1][m][1] * rs + su1;
;                 f32x4 h0, h1;
;                 { const f32x2 a = swiglu_pk((f32x2){g0[0], g0[1]}, (f32x2){u0[0], u0[1]}), b2 = swiglu_pk((f32x2){g0[2], g0[3]}, (f32x2){u0[2], u0[3]});
;                   const f32x2 c = swiglu_pk((f32x2){g1[0], g1[1]}, (f32x2){u1[0], u1[1]}), d = swiglu_pk((f32x2){g1[2], g1[3]}, (f32x2){u1[2], u1[3]});
;                   h0 = (f32x4){a.x, a.y, b2.x, b2.y}; h1 = (f32x4){c.x, c.y, d.x, d.y}; }
;                 u32x4 w; w.x = cvt_pk_bf16(h0[0], h0[1]); w.y = cvt_pk_bf16(h0[2], h0[3]); w.z = cvt_pk_bf16(h1[0], h1[1]); w.w = cvt_pk_bf16(h1[2], h1[3]);
;                 *(gs_u32x4*)(PG8_GPTR(O) + (unsigned)(row * FFN + col0) * 2u) = w;
;             }
.LBB0_1174:
	s_lshl_b32 s2, s28, 8
	v_mbcnt_lo_u32_b32 v0, -1, 0
	v_mbcnt_hi_u32_b32 v0, -1, v0
	s_add_i32 s2, s2, s47
	v_and_b32_e32 v160, 15, v0
	v_or_b32_e32 v167, s2, v160
	s_lshl_b32 s2, s52, 11
	s_and_b32 s2, s2, 0x800
	s_add_i32 s2, s2, 0
	v_lshrrev_b32_e32 v0, 1, v0
	s_add_i32 s2, s2, 0x21400
	s_lshl_b32 s3, s48, 2
	v_and_b32_e32 v0, 24, v0
	s_add_i32 s3, s2, s3
	v_lshl_add_u32 v90, v0, 2, s3
	s_lshl_b32 s3, s47, 2
	s_add_i32 s2, s2, s3
	v_lshl_add_u32 v160, v160, 2, s2
	ds_read_b128 v[106:109], v90 offset:1024
	ds_read_b128 v[102:105], v90 offset:1040
	ds_read_b128 v[98:101], v90 offset:1536
	ds_read_b128 v[90:93], v90 offset:1552
	ds_read2_b32 v[168:169], v160 offset1:16
	ds_read2_b32 v[164:165], v160 offset0:32 offset1:48
	ds_read2_b32 v[162:163], v160 offset0:128 offset1:144
	ds_read2_b32 v[160:161], v160 offset0:160 offset1:176
	s_lshl_b32 s2, s26, 7
	s_waitcnt lgkmcnt(0)
	v_pk_fma_f32 v[146:147], v[146:147], v[168:169], v[106:107] op_sel_hi:[1,0,1]
	v_pk_fma_f32 v[148:149], v[148:149], v[168:169], v[108:109] op_sel_hi:[1,0,1]
	v_pk_mul_f32 v[170:171], v[146:147], s[84:85] op_sel_hi:[1,0]
	v_pk_fma_f32 v[138:139], v[138:139], v[168:169], v[98:99] op_sel_hi:[1,0,1]
	v_exp_f32_e32 v170, v170
	v_exp_f32_e32 v171, v171
	v_pk_fma_f32 v[142:143], v[142:143], v[168:169], v[102:103] op_sel_hi:[1,0,1]
	v_pk_fma_f32 v[140:141], v[140:141], v[168:169], v[100:101] op_sel_hi:[1,0,1]
	v_pk_fma_f32 v[144:145], v[144:145], v[168:169], v[104:105] op_sel_hi:[1,0,1]
	v_pk_add_f32 v[170:171], v[170:171], 1.0 op_sel_hi:[1,0]
	v_pk_fma_f32 v[134:135], v[134:135], v[168:169], v[90:91] op_sel_hi:[1,0,1]
	v_rcp_f32_e32 v170, v170
	v_rcp_f32_e32 v171, v171
	s_or_b32 s2, s2, s48
	v_or_b32_e32 v0, s2, v0
	v_pk_fma_f32 v[136:137], v[136:137], v[168:169], v[92:93] op_sel_hi:[1,0,1]
	v_pk_mul_f32 v[146:147], v[146:147], v[170:171]
	s_movk_i32 s2, 0xb00
	v_pk_mul_f32 v[138:139], v[138:139], v[146:147]
	v_pk_mul_f32 v[146:147], v[148:149], s[84:85] op_sel_hi:[1,0]
	v_pk_fma_f32 v[114:115], v[114:115], v[164:165], v[106:107] op_sel_hi:[1,0,1]
	v_exp_f32_e32 v146, v146
	v_exp_f32_e32 v147, v147
	v_pk_fma_f32 v[116:117], v[116:117], v[164:165], v[108:109] op_sel_hi:[1,0,1]
	v_pk_fma_f32 v[94:95], v[94:95], v[164:165], v[98:99] op_sel_hi:[1,0,1]
	v_pk_fma_f32 v[110:111], v[110:111], v[164:165], v[102:103] op_sel_hi:[1,0,1]
	v_pk_add_f32 v[146:147], v[146:147], 1.0 op_sel_hi:[1,0]
	v_pk_fma_f32 v[96:97], v[96:97], v[164:165], v[100:101] op_sel_hi:[1,0,1]
	v_rcp_f32_e32 v146, v146
	v_rcp_f32_e32 v147, v147
	v_pk_fma_f32 v[112:113], v[112:113], v[164:165], v[104:105] op_sel_hi:[1,0,1]
	v_pk_fma_f32 v[86:87], v[86:87], v[164:165], v[90:91] op_sel_hi:[1,0,1]
	v_pk_fma_f32 v[88:89], v[88:89], v[164:165], v[92:93] op_sel_hi:[1,0,1]
	v_pk_mul_f32 v[146:147], v[148:149], v[146:147]
	v_pk_fma_f32 v[66:67], v[66:67], v[162:163], v[106:107] op_sel_hi:[1,0,1]
	v_pk_mul_f32 v[140:141], v[140:141], v[146:147]
	v_pk_mul_f32 v[146:147], v[142:143], s[84:85] op_sel_hi:[1,0]
	v_pk_fma_f32 v[68:69], v[68:69], v[162:163], v[108:109] op_sel_hi:[1,0,1]
	v_exp_f32_e32 v146, v146
	v_exp_f32_e32 v147, v147
	v_pk_fma_f32 v[58:59], v[58:59], v[162:163], v[98:99] op_sel_hi:[1,0,1]
	v_pk_fma_f32 v[62:63], v[62:63], v[162:163], v[102:103] op_sel_hi:[1,0,1]
	v_pk_fma_f32 v[60:61], v[60:61], v[162:163], v[100:101] op_sel_hi:[1,0,1]
	v_pk_add_f32 v[146:147], v[146:147], 1.0 op_sel_hi:[1,0]
	v_pk_fma_f32 v[64:65], v[64:65], v[162:163], v[104:105] op_sel_hi:[1,0,1]
	v_rcp_f32_e32 v146, v146
	v_rcp_f32_e32 v147, v147
	v_pk_fma_f32 v[54:55], v[54:55], v[162:163], v[90:91] op_sel_hi:[1,0,1]
	v_pk_fma_f32 v[56:57], v[56:57], v[162:163], v[92:93] op_sel_hi:[1,0,1]
	v_pk_fma_f32 v[34:35], v[34:35], v[160:161], v[106:107] op_sel_hi:[1,0,1]
	v_pk_mul_f32 v[142:143], v[142:143], v[146:147]
	v_pk_fma_f32 v[36:37], v[36:37], v[160:161], v[108:109] op_sel_hi:[1,0,1]
	v_pk_mul_f32 v[142:143], v[134:135], v[142:143]
	v_pk_mul_f32 v[134:135], v[144:145], s[84:85] op_sel_hi:[1,0]
	v_pk_fma_f32 v[26:27], v[26:27], v[160:161], v[98:99] op_sel_hi:[1,0,1]
	v_exp_f32_e32 v134, v134
	v_exp_f32_e32 v135, v135
	v_pk_fma_f32 v[30:31], v[30:31], v[160:161], v[102:103] op_sel_hi:[1,0,1]
	v_pk_fma_f32 v[28:29], v[28:29], v[160:161], v[100:101] op_sel_hi:[1,0,1]
	v_pk_fma_f32 v[32:33], v[32:33], v[160:161], v[104:105] op_sel_hi:[1,0,1]
	v_pk_add_f32 v[134:135], v[134:135], 1.0 op_sel_hi:[1,0]
	v_pk_fma_f32 v[22:23], v[22:23], v[160:161], v[90:91] op_sel_hi:[1,0,1]
	v_rcp_f32_e32 v134, v134
	v_rcp_f32_e32 v135, v135
	v_pk_fma_f32 v[24:25], v[24:25], v[160:161], v[92:93] op_sel_hi:[1,0,1]
	s_and_b64 vcc, exec, s[6:7]
	v_pk_mul_f32 v[134:135], v[144:145], v[134:135]
	s_nop 0
	v_pk_mul_f32 v[144:145], v[136:137], v[134:135]
	v_cvt_pk_bf16_f32 v134, v138, v139
	v_mul_lo_u32 v138, v167, s2
	v_lshrrev_b32_e32 v245, 4, v167
	v_mul_u32_u24_e32 v245, 0x16000, v245
	v_and_b32_e32 v247, 15, v167
	v_lshl_add_u32 v245, v247, 6, v245
	v_lshrrev_b32_e32 v247, 5, v0
	v_lshl_add_u32 v245, v247, 10, v245
	v_and_b32_e32 v247, 31, v0
	v_lshl_add_u32 v245, v247, 1, v245
	v_add_lshl_u32 v0, v0, v138, 1
	v_mov_b32_e32 v0, v245
	v_cvt_pk_bf16_f32 v135, v140, v141
	v_cvt_pk_bf16_f32 v136, v142, v143
	v_cvt_pk_bf16_f32 v137, v144, v145
	global_store_dwordx4 v0, v[134:137], s[14:15]
	s_mov_b64 s[2:3], -1
	s_nop 0
	v_mov_b32_e32 v134, v169
	v_pk_fma_f32 v[130:131], v[130:131], v[134:135], v[106:107] op_sel_hi:[1,0,1]
	v_pk_fma_f32 v[132:133], v[132:133], v[134:135], v[108:109] op_sel_hi:[1,0,1]
	v_pk_fma_f32 v[128:129], v[128:129], v[134:135], v[104:105] op_sel_hi:[1,0,1]
	v_pk_fma_f32 v[126:127], v[126:127], v[134:135], v[102:103] op_sel_hi:[1,0,1]
; __device__ __forceinline__ unsigned cvt_pk_bf16(float lo, float hi) { unsigned r; asm volatile("v_cvt_pk_bf16_f32 %0, %1, %2" : "=v"(r) : "v"(lo), "v"(hi)); return r; }
; #define PG8_GPTR(p) ((__attribute__((address_space(1))) char*)(p))
; __device__ __forceinline__ f32x2 swiglu_pk(f32x2 g, f32x2 u) {
;     const f32x2 t = g * (-LOG2E); f32x2 e; e.x = __builtin_amdgcn_exp2f(t.x); e.y = __builtin_amdgcn_exp2f(t.y);
;     const f32x2 d = e + 1.0f; f32x2 r; r.x = __builtin_amdgcn_rcpf(d.x); r.y = __builtin_amdgcn_rcpf(d.y);
;     return (g * r) * u;
; }
;     __device__ __forceinline__ void operator()(const f32x4 (&acc)[2][2][4][2], const Unit& u, int wr, int wc, int fr, int fq, int par, PG8_LAS unsigned char* lds) const {
;     ...
;             for (int m = 0; m < 4; ++m) {
;                 const int row = row0 + ai * HALF + m * 16;
;                 const float rs = rsv[ai * 4 + m];
;                 const f32x4 g0 = acc[ai][0][m][0] * rs + sg0, g1 = acc[ai][0][m][1] * rs + sg1, u0 = acc[ai][1][m][0] * rs + su0, u1 = acc[ai][1][m][1] * rs + su1;
;                 f32x4 h0, h1;
;                 { const f32x2 a = swiglu_pk((f32x2){g0[0], g0[1]}, (f32x2){u0[0], u0[1]}), b2 = swiglu_pk((f32x2){g0[2], g0[3]}, (f32x2){u0[2], u0[3]});
;                   const f32x2 c = swiglu_pk((f32x2){g1[0], g1[1]}, (f32x2){u1[0], u1[1]}), d = swiglu_pk((f32x2){g1[2], g1[3]}, (f32x2){u1[2], u1[3]});
;                   h0 = (f32x4){a.x, a.y, b2.x, b2.y}; h1 = (f32x4){c.x, c.y, d.x, d.y}; }
;                 u32x4 w; w.x = cvt_pk_bf16(h0[0], h0[1]); w.y = cvt_pk_bf16(h0[2], h0[3]); w.z = cvt_pk_bf16(h1[0], h1[1]); w.w = cvt_pk_bf16(h1[2], h1[3]);
;                 *(gs_u32x4*)(PG8_GPTR(O) + (unsigned)(row * FFN + col0) * 2u) = w;
	v_pk_fma_f32 v[124:125], v[124:125], v[134:135], v[100:101] op_sel_hi:[1,0,1]
	v_pk_fma_f32 v[122:123], v[122:123], v[134:135], v[98:99] op_sel_hi:[1,0,1]
	v_pk_fma_f32 v[120:121], v[120:121], v[134:135], v[92:93] op_sel_hi:[1,0,1]
	v_pk_fma_f32 v[118:119], v[118:119], v[134:135], v[90:91] op_sel_hi:[1,0,1]
	v_pk_mul_f32 v[134:135], v[130:131], s[84:85] op_sel_hi:[1,0]
	s_nop 0
	v_exp_f32_e32 v134, v134
	v_exp_f32_e32 v135, v135
	s_nop 0
	v_pk_add_f32 v[134:135], v[134:135], 1.0 op_sel_hi:[1,0]
	s_nop 0
	v_rcp_f32_e32 v134, v134
	v_rcp_f32_e32 v135, v135
	s_nop 0
	v_pk_mul_f32 v[130:131], v[130:131], v[134:135]
	s_nop 0
	v_pk_mul_f32 v[122:123], v[122:123], v[130:131]
	v_pk_mul_f32 v[130:131], v[132:133], s[84:85] op_sel_hi:[1,0]
	s_nop 0
	v_exp_f32_e32 v130, v130
	v_exp_f32_e32 v131, v131
	s_nop 0
	v_pk_add_f32 v[130:131], v[130:131], 1.0 op_sel_hi:[1,0]
	s_nop 0
	v_rcp_f32_e32 v130, v130
	v_rcp_f32_e32 v131, v131
	s_nop 0
	v_pk_mul_f32 v[130:131], v[132:133], v[130:131]
	s_nop 0
	v_pk_mul_f32 v[124:125], v[124:125], v[130:131]
	v_pk_mul_f32 v[130:131], v[126:127], s[84:85] op_sel_hi:[1,0]
	s_nop 0
	v_exp_f32_e32 v130, v130
	v_exp_f32_e32 v131, v131
	s_nop 0
	v_pk_add_f32 v[130:131], v[130:131], 1.0 op_sel_hi:[1,0]
	s_nop 0
	v_rcp_f32_e32 v130, v130
	v_rcp_f32_e32 v131, v131
	s_nop 0
	v_pk_mul_f32 v[126:127], v[126:127], v[130:131]
	s_nop 0
	v_pk_mul_f32 v[126:127], v[118:119], v[126:127]
	v_pk_mul_f32 v[118:119], v[128:129], s[84:85] op_sel_hi:[1,0]
	s_nop 0
	v_exp_f32_e32 v118, v118
	v_exp_f32_e32 v119, v119
	s_nop 0
	v_pk_add_f32 v[118:119], v[118:119], 1.0 op_sel_hi:[1,0]
	s_nop 0
	v_rcp_f32_e32 v118, v118
	v_rcp_f32_e32 v119, v119
	s_nop 0
	v_pk_mul_f32 v[118:119], v[128:129], v[118:119]
	s_nop 0
	v_pk_mul_f32 v[128:129], v[120:121], v[118:119]
	v_cvt_pk_bf16_f32 v118, v122, v123
	v_cvt_pk_bf16_f32 v119, v124, v125
	v_add_u32_e32 v122, 0x16000, v0
	v_cvt_pk_bf16_f32 v120, v126, v127
	v_cvt_pk_bf16_f32 v121, v128, v129
	global_store_dwordx4 v122, v[118:121], s[14:15]
	s_nop 1
	v_pk_mul_f32 v[118:119], v[114:115], s[84:85] op_sel_hi:[1,0]
	s_nop 0
	v_exp_f32_e32 v118, v118
	v_exp_f32_e32 v119, v119
	s_nop 0
	v_pk_add_f32 v[118:119], v[118:119], 1.0 op_sel_hi:[1,0]
	s_nop 0
	v_rcp_f32_e32 v118, v118
	v_rcp_f32_e32 v119, v119
	s_nop 0
	v_pk_mul_f32 v[114:115], v[114:115], v[118:119]
	s_nop 0
	v_pk_mul_f32 v[94:95], v[94:95], v[114:115]
	v_pk_mul_f32 v[114:115], v[116:117], s[84:85] op_sel_hi:[1,0]
	s_nop 0
	v_exp_f32_e32 v114, v114
	v_exp_f32_e32 v115, v115
	s_nop 0
	v_pk_add_f32 v[114:115], v[114:115], 1.0 op_sel_hi:[1,0]
	s_nop 0
	v_rcp_f32_e32 v114, v114
	v_rcp_f32_e32 v115, v115
	s_nop 0
	v_pk_mul_f32 v[114:115], v[116:117], v[114:115]
	s_nop 0
	v_pk_mul_f32 v[96:97], v[96:97], v[114:115]
	v_pk_mul_f32 v[114:115], v[110:111], s[84:85] op_sel_hi:[1,0]
	s_nop 0
	v_exp_f32_e32 v114, v114
	v_exp_f32_e32 v115, v115
	s_nop 0
	v_pk_add_f32 v[114:115], v[114:115], 1.0 op_sel_hi:[1,0]
	s_nop 0
	v_rcp_f32_e32 v114, v114
	v_rcp_f32_e32 v115, v115
	s_nop 0
	v_pk_mul_f32 v[110:111], v[110:111], v[114:115]
	s_nop 0
	v_pk_mul_f32 v[110:111], v[86:87], v[110:111]
	v_pk_mul_f32 v[86:87], v[112:113], s[84:85] op_sel_hi:[1,0]
	s_nop 0
	v_exp_f32_e32 v86, v86
	v_exp_f32_e32 v87, v87
	s_nop 0
	v_pk_add_f32 v[86:87], v[86:87], 1.0 op_sel_hi:[1,0]
	s_nop 0
	v_rcp_f32_e32 v86, v86
	v_rcp_f32_e32 v87, v87
	s_nop 0
	v_pk_mul_f32 v[86:87], v[112:113], v[86:87]
	s_nop 0
	v_pk_mul_f32 v[112:113], v[88:89], v[86:87]
	v_cvt_pk_bf16_f32 v86, v94, v95
	v_add_u32_e32 v94, 0x2c000, v0
	v_cvt_pk_bf16_f32 v87, v96, v97
	v_cvt_pk_bf16_f32 v88, v110, v111
	v_cvt_pk_bf16_f32 v89, v112, v113
	global_store_dwordx4 v94, v[86:89], s[14:15]
	s_nop 1
	v_mov_b32_e32 v86, v165
	v_pk_fma_f32 v[82:83], v[82:83], v[86:87], v[106:107] op_sel_hi:[1,0,1]
	v_pk_fma_f32 v[84:85], v[84:85], v[86:87], v[108:109] op_sel_hi:[1,0,1]
	v_pk_fma_f32 v[80:81], v[80:81], v[86:87], v[104:105] op_sel_hi:[1,0,1]
	v_pk_fma_f32 v[78:79], v[78:79], v[86:87], v[102:103] op_sel_hi:[1,0,1]
	v_pk_fma_f32 v[76:77], v[76:77], v[86:87], v[100:101] op_sel_hi:[1,0,1]
	v_pk_fma_f32 v[74:75], v[74:75], v[86:87], v[98:99] op_sel_hi:[1,0,1]
	v_pk_fma_f32 v[72:73], v[72:73], v[86:87], v[92:93] op_sel_hi:[1,0,1]
	v_pk_fma_f32 v[70:71], v[70:71], v[86:87], v[90:91] op_sel_hi:[1,0,1]
	v_pk_mul_f32 v[86:87], v[82:83], s[84:85] op_sel_hi:[1,0]
	s_nop 0
	v_exp_f32_e32 v86, v86
	v_exp_f32_e32 v87, v87
	s_nop 0
	v_pk_add_f32 v[86:87], v[86:87], 1.0 op_sel_hi:[1,0]
	s_nop 0
	v_rcp_f32_e32 v86, v86
	v_rcp_f32_e32 v87, v87
	s_nop 0
	v_pk_mul_f32 v[82:83], v[82:83], v[86:87]
	s_nop 0
	v_pk_mul_f32 v[74:75], v[74:75], v[82:83]
	v_pk_mul_f32 v[82:83], v[84:85], s[84:85] op_sel_hi:[1,0]
	s_nop 0
	v_exp_f32_e32 v82, v82
	v_exp_f32_e32 v83, v83
	s_nop 0
	v_pk_add_f32 v[82:83], v[82:83], 1.0 op_sel_hi:[1,0]
	s_nop 0
	v_rcp_f32_e32 v82, v82
	v_rcp_f32_e32 v83, v83
	s_nop 0
	v_pk_mul_f32 v[82:83], v[84:85], v[82:83]
	s_nop 0
	v_pk_mul_f32 v[76:77], v[76:77], v[82:83]
	v_pk_mul_f32 v[82:83], v[78:79], s[84:85] op_sel_hi:[1,0]
	s_nop 0
	v_exp_f32_e32 v82, v82
	v_exp_f32_e32 v83, v83
	s_nop 0
	v_pk_add_f32 v[82:83], v[82:83], 1.0 op_sel_hi:[1,0]
	s_nop 0
	v_rcp_f32_e32 v82, v82
	v_rcp_f32_e32 v83, v83
	s_nop 0
	v_pk_mul_f32 v[78:79], v[78:79], v[82:83]
	s_nop 0
	v_pk_mul_f32 v[78:79], v[70:71], v[78:79]
	v_pk_mul_f32 v[70:71], v[80:81], s[84:85] op_sel_hi:[1,0]
	s_nop 0
	v_exp_f32_e32 v70, v70
	v_exp_f32_e32 v71, v71
	s_nop 0
	v_pk_add_f32 v[70:71], v[70:71], 1.0 op_sel_hi:[1,0]
	s_nop 0
	v_rcp_f32_e32 v70, v70
	v_rcp_f32_e32 v71, v71
	s_nop 0
	v_pk_mul_f32 v[70:71], v[80:81], v[70:71]
	s_nop 0
	v_pk_mul_f32 v[80:81], v[72:73], v[70:71]
; __device__ __forceinline__ unsigned cvt_pk_bf16(float lo, float hi) { unsigned r; asm volatile("v_cvt_pk_bf16_f32 %0, %1, %2" : "=v"(r) : "v"(lo), "v"(hi)); return r; }
; #define PG8_GPTR(p) ((__attribute__((address_space(1))) char*)(p))
; __device__ __forceinline__ f32x2 swiglu_pk(f32x2 g, f32x2 u) {
;     const f32x2 t = g * (-LOG2E); f32x2 e; e.x = __builtin_amdgcn_exp2f(t.x); e.y = __builtin_amdgcn_exp2f(t.y);
;     const f32x2 d = e + 1.0f; f32x2 r; r.x = __builtin_amdgcn_rcpf(d.x); r.y = __builtin_amdgcn_rcpf(d.y);
;     return (g * r) * u;
; }
;     __device__ __forceinline__ void operator()(const f32x4 (&acc)[2][2][4][2], const Unit& u, int wr, int wc, int fr, int fq, int par, PG8_LAS unsigned char* lds) const {
;     ...
;             for (int m = 0; m < 4; ++m) {
;                 const int row = row0 + ai * HALF + m * 16;
;                 const float rs = rsv[ai * 4 + m];
;                 const f32x4 g0 = acc[ai][0][m][0] * rs + sg0, g1 = acc[ai][0][m][1] * rs + sg1, u0 = acc[ai][1][m][0] * rs + su0, u1 = acc[ai][1][m][1] * rs + su1;
;                 f32x4 h0, h1;
;                 { const f32x2 a = swiglu_pk((f32x2){g0[0], g0[1]}, (f32x2){u0[0], u0[1]}), b2 = swiglu_pk((f32x2){g0[2], g0[3]}, (f32x2){u0[2], u0[3]});
;                   const f32x2 c = swiglu_pk((f32x2){g1[0], g1[1]}, (f32x2){u1[0], u1[1]}), d = swiglu_pk((f32x2){g1[2], g1[3]}, (f32x2){u1[2], u1[3]});
;                   h0 = (f32x4){a.x, a.y, b2.x, b2.y}; h1 = (f32x4){c.x, c.y, d.x, d.y}; }
;                 u32x4 w; w.x = cvt_pk_bf16(h0[0], h0[1]); w.y = cvt_pk_bf16(h0[2], h0[3]); w.z = cvt_pk_bf16(h1[0], h1[1]); w.w = cvt_pk_bf16(h1[2], h1[3]);
;                 *(gs_u32x4*)(PG8_GPTR(O) + (unsigned)(row * FFN + col0) * 2u) = w;
	v_cvt_pk_bf16_f32 v70, v74, v75
	v_cvt_pk_bf16_f32 v71, v76, v77
	v_add_u32_e32 v74, 0x42000, v0
	v_cvt_pk_bf16_f32 v72, v78, v79
	v_cvt_pk_bf16_f32 v73, v80, v81
	global_store_dwordx4 v74, v[70:73], s[14:15]
	s_nop 1
	v_pk_mul_f32 v[70:71], v[66:67], s[84:85] op_sel_hi:[1,0]
	s_nop 0
	v_exp_f32_e32 v70, v70
	v_exp_f32_e32 v71, v71
	s_nop 0
	v_pk_add_f32 v[70:71], v[70:71], 1.0 op_sel_hi:[1,0]
	s_nop 0
	v_rcp_f32_e32 v70, v70
	v_rcp_f32_e32 v71, v71
	s_nop 0
	v_pk_mul_f32 v[66:67], v[66:67], v[70:71]
	s_nop 0
	v_pk_mul_f32 v[58:59], v[58:59], v[66:67]
	v_pk_mul_f32 v[66:67], v[68:69], s[84:85] op_sel_hi:[1,0]
	s_nop 0
	v_exp_f32_e32 v66, v66
	v_exp_f32_e32 v67, v67
	s_nop 0
	v_pk_add_f32 v[66:67], v[66:67], 1.0 op_sel_hi:[1,0]
	s_nop 0
	v_rcp_f32_e32 v66, v66
	v_rcp_f32_e32 v67, v67
	s_nop 0
	v_pk_mul_f32 v[66:67], v[68:69], v[66:67]
	s_nop 0
	v_pk_mul_f32 v[60:61], v[60:61], v[66:67]
	v_pk_mul_f32 v[66:67], v[62:63], s[84:85] op_sel_hi:[1,0]
	s_nop 0
	v_exp_f32_e32 v66, v66
	v_exp_f32_e32 v67, v67
	s_nop 0
	v_pk_add_f32 v[66:67], v[66:67], 1.0 op_sel_hi:[1,0]
	s_nop 0
	v_rcp_f32_e32 v66, v66
	v_rcp_f32_e32 v67, v67
	s_nop 0
	v_pk_mul_f32 v[62:63], v[62:63], v[66:67]
	s_nop 0
	v_pk_mul_f32 v[62:63], v[54:55], v[62:63]
	v_pk_mul_f32 v[54:55], v[64:65], s[84:85] op_sel_hi:[1,0]
	s_nop 0
	v_exp_f32_e32 v54, v54
	v_exp_f32_e32 v55, v55
	s_nop 0
	v_pk_add_f32 v[54:55], v[54:55], 1.0 op_sel_hi:[1,0]
	s_nop 0
	v_rcp_f32_e32 v54, v54
	v_rcp_f32_e32 v55, v55
	s_nop 0
	v_pk_mul_f32 v[54:55], v[64:65], v[54:55]
	s_nop 0
	v_pk_mul_f32 v[64:65], v[56:57], v[54:55]
	v_cvt_pk_bf16_f32 v54, v58, v59
	v_add_u32_e32 v58, 0xb0000, v0
	v_cvt_pk_bf16_f32 v55, v60, v61
	v_cvt_pk_bf16_f32 v56, v62, v63
	v_cvt_pk_bf16_f32 v57, v64, v65
	global_store_dwordx4 v58, v[54:57], s[14:15]
	s_nop 1
	v_mov_b32_e32 v54, v163
	v_pk_fma_f32 v[50:51], v[50:51], v[54:55], v[106:107] op_sel_hi:[1,0,1]
	v_pk_fma_f32 v[52:53], v[52:53], v[54:55], v[108:109] op_sel_hi:[1,0,1]
	v_pk_fma_f32 v[48:49], v[48:49], v[54:55], v[104:105] op_sel_hi:[1,0,1]
	v_pk_fma_f32 v[46:47], v[46:47], v[54:55], v[102:103] op_sel_hi:[1,0,1]
	v_pk_fma_f32 v[44:45], v[44:45], v[54:55], v[100:101] op_sel_hi:[1,0,1]
	v_pk_fma_f32 v[42:43], v[42:43], v[54:55], v[98:99] op_sel_hi:[1,0,1]
	v_pk_fma_f32 v[40:41], v[40:41], v[54:55], v[92:93] op_sel_hi:[1,0,1]
	v_pk_fma_f32 v[38:39], v[38:39], v[54:55], v[90:91] op_sel_hi:[1,0,1]
	v_pk_mul_f32 v[54:55], v[50:51], s[84:85] op_sel_hi:[1,0]
	s_nop 0
	v_exp_f32_e32 v54, v54
	v_exp_f32_e32 v55, v55
	s_nop 0
	v_pk_add_f32 v[54:55], v[54:55], 1.0 op_sel_hi:[1,0]
	s_nop 0
	v_rcp_f32_e32 v54, v54
	v_rcp_f32_e32 v55, v55
	s_nop 0
	v_pk_mul_f32 v[50:51], v[50:51], v[54:55]
	s_nop 0
	v_pk_mul_f32 v[42:43], v[42:43], v[50:51]
	v_pk_mul_f32 v[50:51], v[52:53], s[84:85] op_sel_hi:[1,0]
	s_nop 0
	v_exp_f32_e32 v50, v50
	v_exp_f32_e32 v51, v51
	s_nop 0
	v_pk_add_f32 v[50:51], v[50:51], 1.0 op_sel_hi:[1,0]
	s_nop 0
	v_rcp_f32_e32 v50, v50
	v_rcp_f32_e32 v51, v51
	s_nop 0
	v_pk_mul_f32 v[50:51], v[52:53], v[50:51]
	s_nop 0
	v_pk_mul_f32 v[44:45], v[44:45], v[50:51]
	v_pk_mul_f32 v[50:51], v[46:47], s[84:85] op_sel_hi:[1,0]
	s_nop 0
	v_exp_f32_e32 v50, v50
	v_exp_f32_e32 v51, v51
	s_nop 0
	v_pk_add_f32 v[50:51], v[50:51], 1.0 op_sel_hi:[1,0]
	s_nop 0
	v_rcp_f32_e32 v50, v50
	v_rcp_f32_e32 v51, v51
	s_nop 0
	v_pk_mul_f32 v[46:47], v[46:47], v[50:51]
	s_nop 0
	v_pk_mul_f32 v[46:47], v[38:39], v[46:47]
	v_pk_mul_f32 v[38:39], v[48:49], s[84:85] op_sel_hi:[1,0]
	s_nop 0
	v_exp_f32_e32 v38, v38
	v_exp_f32_e32 v39, v39
	s_nop 0
	v_pk_add_f32 v[38:39], v[38:39], 1.0 op_sel_hi:[1,0]
	s_nop 0
	v_rcp_f32_e32 v38, v38
	v_rcp_f32_e32 v39, v39
	s_nop 0
	v_pk_mul_f32 v[38:39], v[48:49], v[38:39]
	s_nop 0
	v_pk_mul_f32 v[48:49], v[40:41], v[38:39]
	v_cvt_pk_bf16_f32 v38, v42, v43
	v_cvt_pk_bf16_f32 v39, v44, v45
	v_add_u32_e32 v42, 0xc6000, v0
	v_cvt_pk_bf16_f32 v40, v46, v47
; #define PG8_BAR __builtin_amdgcn_s_barrier()
; #define PG8_GPTR(p) ((__attribute__((address_space(1))) char*)(p))
; template <class Epi, class Sched, bool ALIGN_EPI = false, bool SP2 = false>
; __device__ __forceinline__ void gemm_phase(PG8_LAS unsigned char* lds, const Gemm g, const Sched& S, const Epi& E, const int wave_s) {
;     ...
;         if constexpr (ALIGN_EPI) { if (wr == 0) PG8_BAR; }
;         if constexpr (Epi::KHOOK || Epi::PREF) { if (has_next) E.prefetch(nxt, (ui + 1) & 1, lds, opaque_tid(wave_s)); }
;         if constexpr (!Epi::AFTER_DRAIN) { const int l2_ = opaque_tid(wave_s) & 63;
;             if constexpr (Epi::PREF) E(acc, cur, wr, wc, l2_ & 15, l2_ >> 4, ui & 1, lds); else E(acc, cur, wr, wc, l2_ & 15, l2_ >> 4);
;             S.done(cur); }
;         if (!has_next) break;
; #pragma unroll
;         for (int a = 0; a < 2; ++a)
; #pragma unroll
;             for (int b = 0; b < 2; ++b)
; #pragma unroll
;                 for (int m = 0; m < 4; ++m)
; #pragma unroll
;                     for (int n = 0; n < 2; ++n) acc[a][b][m][n] = (f32x4){0.f, 0.f, 0.f, 0.f};
;         cur = nxt; cA = nA; cB = nB; ++ui;
;         if constexpr (ALIGN_EPI) { if (wr == 1) PG8_BAR; }
;     }
;     __device__ __forceinline__ void operator()(const f32x4 (&acc)[2][2][4][2], const Unit& u, int wr, int wc, int fr, int fq, int par, PG8_LAS unsigned char* lds) const {
;     ...
;             for (int m = 0; m < 4; ++m) {
;                 const int row = row0 + ai * HALF + m * 16;
;                 const float rs = rsv[ai * 4 + m];
;                 const f32x4 g0 = acc[ai][0][m][0] * rs + sg0, g1 = acc[ai][0][m][1] * rs + sg1, u0 = acc[ai][1][m][0] * rs + su0, u1 = acc[ai][1][m][1] * rs + su1;
;                 f32x4 h0, h1;
;                 { const f32x2 a = swiglu_pk((f32x2){g0[0], g0[1]}, (f32x2){u0[0], u0[1]}), b2 = swiglu_pk((f32x2){g0[2], g0[3]}, (f32x2){u0[2], u0[3]});
;                   const f32x2 c = swiglu_pk((f32x2){g1[0], g1[1]}, (f32x2){u1[0], u1[1]}), d = swiglu_pk((f32x2){g1[2], g1[3]}, (f32x2){u1[2], u1[3]});
;                   h0 = (f32x4){a.x, a.y, b2.x, b2.y}; h1 = (f32x4){c.x, c.y, d.x, d.y}; }
;                 u32x4 w; w.x = cvt_pk_bf16(h0[0], h0[1]); w.y = cvt_pk_bf16(h0[2], h0[3]); w.z = cvt_pk_bf16(h1[0], h1[1]); w.w = cvt_pk_bf16(h1[2], h1[3]);
;                 *(gs_u32x4*)(PG8_GPTR(O) + (unsigned)(row * FFN + col0) * 2u) = w;
;             }
	v_cvt_pk_bf16_f32 v41, v48, v49
	global_store_dwordx4 v42, v[38:41], s[14:15]
	s_nop 1
	v_pk_mul_f32 v[38:39], v[34:35], s[84:85] op_sel_hi:[1,0]
	s_nop 0
	v_exp_f32_e32 v38, v38
	v_exp_f32_e32 v39, v39
	s_nop 0
	v_pk_add_f32 v[38:39], v[38:39], 1.0 op_sel_hi:[1,0]
	s_nop 0
	v_rcp_f32_e32 v38, v38
	v_rcp_f32_e32 v39, v39
	s_nop 0
	v_pk_mul_f32 v[34:35], v[34:35], v[38:39]
	s_nop 0
	v_pk_mul_f32 v[26:27], v[26:27], v[34:35]
	v_pk_mul_f32 v[34:35], v[36:37], s[84:85] op_sel_hi:[1,0]
	s_nop 0
	v_exp_f32_e32 v34, v34
	v_exp_f32_e32 v35, v35
	s_nop 0
	v_pk_add_f32 v[34:35], v[34:35], 1.0 op_sel_hi:[1,0]
	s_nop 0
	v_rcp_f32_e32 v34, v34
	v_rcp_f32_e32 v35, v35
	s_nop 0
	v_pk_mul_f32 v[34:35], v[36:37], v[34:35]
	s_nop 0
	v_pk_mul_f32 v[28:29], v[28:29], v[34:35]
	v_pk_mul_f32 v[34:35], v[30:31], s[84:85] op_sel_hi:[1,0]
	s_nop 0
	v_exp_f32_e32 v34, v34
	v_exp_f32_e32 v35, v35
	s_nop 0
	v_pk_add_f32 v[34:35], v[34:35], 1.0 op_sel_hi:[1,0]
	s_nop 0
	v_rcp_f32_e32 v34, v34
	v_rcp_f32_e32 v35, v35
	s_nop 0
	v_pk_mul_f32 v[30:31], v[30:31], v[34:35]
	s_nop 0
	v_pk_mul_f32 v[30:31], v[22:23], v[30:31]
	v_pk_mul_f32 v[22:23], v[32:33], s[84:85] op_sel_hi:[1,0]
	s_nop 0
	v_exp_f32_e32 v22, v22
	v_exp_f32_e32 v23, v23
	s_nop 0
	v_pk_add_f32 v[22:23], v[22:23], 1.0 op_sel_hi:[1,0]
	s_nop 0
	v_rcp_f32_e32 v22, v22
	v_rcp_f32_e32 v23, v23
	s_nop 0
	v_pk_mul_f32 v[22:23], v[32:33], v[22:23]
	s_nop 0
	v_pk_mul_f32 v[32:33], v[24:25], v[22:23]
	v_cvt_pk_bf16_f32 v22, v26, v27
	v_add_u32_e32 v26, 0xdc000, v0
	v_cvt_pk_bf16_f32 v23, v28, v29
	v_cvt_pk_bf16_f32 v24, v30, v31
	v_cvt_pk_bf16_f32 v25, v32, v33
	global_store_dwordx4 v26, v[22:25], s[14:15]
	v_add_u32_e32 v0, 0xf2000, v0
	s_nop 0
	v_mov_b32_e32 v22, v161
	v_pk_fma_f32 v[18:19], v[18:19], v[22:23], v[106:107] op_sel_hi:[1,0,1]
	v_pk_fma_f32 v[20:21], v[20:21], v[22:23], v[108:109] op_sel_hi:[1,0,1]
	v_pk_fma_f32 v[12:13], v[12:13], v[22:23], v[104:105] op_sel_hi:[1,0,1]
	v_pk_fma_f32 v[10:11], v[10:11], v[22:23], v[102:103] op_sel_hi:[1,0,1]
	v_pk_fma_f32 v[8:9], v[8:9], v[22:23], v[100:101] op_sel_hi:[1,0,1]
	v_pk_fma_f32 v[6:7], v[6:7], v[22:23], v[98:99] op_sel_hi:[1,0,1]
	v_pk_fma_f32 v[4:5], v[4:5], v[22:23], v[92:93] op_sel_hi:[1,0,1]
	v_pk_fma_f32 v[2:3], v[2:3], v[22:23], v[90:91] op_sel_hi:[1,0,1]
	v_pk_mul_f32 v[22:23], v[18:19], s[84:85] op_sel_hi:[1,0]
	s_nop 0
	v_exp_f32_e32 v22, v22
	v_exp_f32_e32 v23, v23
	s_nop 0
	v_pk_add_f32 v[22:23], v[22:23], 1.0 op_sel_hi:[1,0]
	s_nop 0
	v_rcp_f32_e32 v22, v22
	v_rcp_f32_e32 v23, v23
	s_nop 0
	v_pk_mul_f32 v[18:19], v[18:19], v[22:23]
	s_nop 0
	v_pk_mul_f32 v[6:7], v[6:7], v[18:19]
	v_pk_mul_f32 v[18:19], v[20:21], s[84:85] op_sel_hi:[1,0]
	s_nop 0
	v_exp_f32_e32 v18, v18
	v_exp_f32_e32 v19, v19
	s_nop 0
	v_pk_add_f32 v[18:19], v[18:19], 1.0 op_sel_hi:[1,0]
	s_nop 0
	v_rcp_f32_e32 v18, v18
	v_rcp_f32_e32 v19, v19
	s_nop 0
	v_pk_mul_f32 v[18:19], v[20:21], v[18:19]
	s_nop 0
	v_pk_mul_f32 v[8:9], v[8:9], v[18:19]
	v_pk_mul_f32 v[18:19], v[10:11], s[84:85] op_sel_hi:[1,0]
	s_nop 0
	v_exp_f32_e32 v18, v18
	v_exp_f32_e32 v19, v19
	s_nop 0
	v_pk_add_f32 v[18:19], v[18:19], 1.0 op_sel_hi:[1,0]
	s_nop 0
	v_rcp_f32_e32 v18, v18
	v_rcp_f32_e32 v19, v19
	s_nop 0
	v_pk_mul_f32 v[10:11], v[10:11], v[18:19]
	s_nop 0
	v_pk_mul_f32 v[10:11], v[2:3], v[10:11]
	v_pk_mul_f32 v[2:3], v[12:13], s[84:85] op_sel_hi:[1,0]
	s_nop 0
	v_exp_f32_e32 v2, v2
	v_exp_f32_e32 v3, v3
	s_nop 0
	v_pk_add_f32 v[2:3], v[2:3], 1.0 op_sel_hi:[1,0]
	s_nop 0
	v_rcp_f32_e32 v2, v2
	v_rcp_f32_e32 v3, v3
	s_nop 0
	v_pk_mul_f32 v[2:3], v[12:13], v[2:3]
	s_nop 0
	v_pk_mul_f32 v[12:13], v[4:5], v[2:3]
	v_cvt_pk_bf16_f32 v2, v6, v7
	v_cvt_pk_bf16_f32 v3, v8, v9
	v_cvt_pk_bf16_f32 v4, v10, v11
	s_nop 0
	v_cvt_pk_bf16_f32 v5, v12, v13
	global_store_dwordx4 v0, v[2:5], s[14:15]
	s_cbranch_vccnz .LBB0_1161
	s_andn2_b64 vcc, exec, s[12:13]
	s_cbranch_vccnz .LBB0_1160
	s_barrier
	s_branch .LBB0_1160

; #define PG8_STAGE(bufoff, gbase, voff) do { _Pragma("unroll") for (int _i = 0; _i < 2; ++_i) \
;         __builtin_amdgcn_global_load_lds((const unsigned*)((const char*)(gbase) + (voff)[_i]), (PG8_LAS unsigned*)(lds + (bufoff) + ldsw + _i * 8192), 16, 0, 0); } while (0)
; #define PG8_WAIT_V(n) asm volatile("s_waitcnt vmcnt(" #n ")" ::: "memory")
; #define PG8_BAR __builtin_amdgcn_s_barrier()
; template <class Epi, class Sched, bool ALIGN_EPI = false, bool SP2 = false>
; __device__ __forceinline__ void gemm_phase(PG8_LAS unsigned char* lds, const Gemm g, const Sched& S, const Epi& E, const int wave_s) {
;     ...
;     for (int i = 0; i < 2; ++i) { int R, C; stage_rc(tid * 16 + i * 8192, R, C); const int Rb = Epi::PERM ? ((R & ~31) + perm32(R & 31)) : R;
;         voffA[i] = (unsigned)(R * g.lda + C) * 2u; voffB[i] = (unsigned)(Rb * K + C) * 2u; }
;     const size_t kstep = (size_t)(BK * 2);
;     const size_t hstepA = (size_t)HALF * g.lda * 2, hstepB = (size_t)HALF * K * 2;
;     const size_t tstepA = 2 * hstepA, tstepB = 2 * hstepB;
;     const unsigned ldsw = (unsigned)wid * 1024u;
;     const int aoff = lds_byte(wr * 64 + fr, fq * 8), boff = lds_byte(wc * 32 + fr, fq * 8);
;     ...
;     if constexpr (SP2) {
;         PG8_STAGE(PG8_SB(0, 0), cB, voffB); PG8_STAGE(PG8_SB(0, 1), cB + hstepB, voffB); PG8_STAGE(PG8_SA(0, 0), cA, voffA); PG8_STAGE(PG8_SA(0, 1), cA + hstepA, voffA);
;         if (wr == 1) PG8_BAR;
;         PG8_WAIT_V(2); PG8_BAR;
;         PG8_STAGE(PG8_SB(1, 0), cB + kstep, voffB); PG8_STAGE(PG8_SA(1, 0), cA + kstep, voffA); PG8_STAGE(PG8_SB(1, 1), cB + hstepB + kstep, voffB);
;         PG8_WAIT_V(6); PG8_BAR;
.LBB0_1226:
	s_andn2_b64 vcc, exec, s[2:3]
	s_add_i32 s66, s30, 1
	s_cbranch_vccnz .LBB0_1306
	v_ashrrev_i32_e32 v3, 31, v0
	v_lshrrev_b32_e32 v3, 26, v3
	v_lshlrev_b32_e32 v2, 4, v0
	v_add_u32_e32 v3, v0, v3
	v_bfe_i32 v0, v0, 27, 1
	v_lshrrev_b32_e32 v0, 22, v0
	v_add_u32_e32 v0, v2, v0
	v_and_b32_e32 v0, 0xfffffc00, v0
	v_sub_u32_e32 v0, v2, v0
	v_ashrrev_i32_e32 v10, 6, v3
	v_lshrrev_b32_e32 v3, 4, v0
	v_bitop3_b32 v0, v3, v0, 32 bitop3:0x6c
	v_ashrrev_i32_e32 v4, 31, v0
	v_lshrrev_b32_e32 v4, 26, v4
	v_lshlrev_b32_e32 v3, 3, v10
	v_add_u32_e32 v4, v0, v4
	v_and_b32_e32 v3, -16, v3
	v_ashrrev_i32_e32 v12, 6, v4
	v_and_b32_e32 v4, 0xc0, v4
	v_add_u32_e32 v3, v12, v3
	v_lshlrev_b32_e32 v5, 5, v10
	v_sub_u32_e32 v0, v0, v4
	v_mov_b32_e32 v7, 1
	v_and_b32_e32 v11, 32, v5
	v_ashrrev_i16_sdwa v0, v7, sext(v0) dst_sel:DWORD dst_unused:UNUSED_PAD src0_sel:DWORD src1_sel:BYTE_0
	v_lshlrev_b32_e32 v4, 1, v3
	v_lshrrev_b32_e32 v5, 2, v3
	v_and_b32_e32 v6, 3, v12
	s_mov_b32 s22, 0xffffe0
	v_bfe_i32 v13, v0, 0, 16
	v_and_b32_e32 v4, 24, v4
	v_and_b32_e32 v5, 4, v5
	v_and_or_b32 v6, v3, s22, v6
	s_movk_i32 s3, 0xb00
	v_add_u32_e32 v0, v11, v13
	v_or3_b32 v4, v6, v5, v4
	v_mov_b32_e32 v244, v3
	v_mov_b32_e32 v248, 0x800
	v_mov_b32_e32 v249, 0
	v_mul_lo_u32 v3, v3, s3
	v_add_lshl_u32 v14, v0, v3, 1
	v_lshrrev_b32_e32 v245, 4, v244
	v_mul_u32_u24_e32 v245, 0x16000, v245
	v_and_b32_e32 v247, 15, v244
	v_lshl_add_u32 v245, v247, 6, v245
	v_lshrrev_b32_e32 v247, 5, v0
	v_lshl_add_u32 v245, v247, 10, v245
	v_and_b32_e32 v247, 31, v0
	v_lshl_add_u32 v245, v247, 1, v245
	v_mov_b32_e32 v14, v245
	v_mul_u32_u24_e32 v3, 0xb00, v4
	v_add_u32_e32 v2, 0x2000, v2
	v_add_lshl_u32 v194, v3, v0, 1
	v_ashrrev_i32_e32 v0, 31, v2
	v_lshrrev_b32_e32 v0, 22, v0
	v_add_u32_e32 v0, v2, v0
	v_ashrrev_i32_e32 v0, 10, v0
	v_mul_i32_i24_e32 v3, 0x400, v0
	v_sub_u32_e32 v2, v2, v3
	v_lshrrev_b32_e32 v3, 4, v2
	v_bitop3_b32 v2, v3, v2, 32 bitop3:0x6c
	v_ashrrev_i32_e32 v4, 31, v2
	v_lshrrev_b32_e32 v4, 26, v4
	v_lshlrev_b32_e32 v3, 3, v0
	v_add_u32_e32 v4, v2, v4
	v_and_b32_e32 v3, -16, v3
	v_ashrrev_i32_e32 v19, 6, v4
	v_add_u32_e32 v3, v19, v3
	v_lshlrev_b32_e32 v5, 5, v0
	v_and_b32_e32 v4, 0xc0, v4
	v_and_b32_e32 v6, 3, v19
	v_and_b32_e32 v18, 32, v5
	v_sub_u32_e32 v2, v2, v4
	v_lshlrev_b32_e32 v4, 1, v3
	v_lshrrev_b32_e32 v5, 2, v3
	v_and_or_b32 v6, v3, s22, v6
	v_mov_b32_e32 v246, v3
	v_mul_lo_u32 v3, v3, s3
	s_ashr_i32 s3, s24, 6
	s_ashr_i32 s2, s24, 8
	s_lshl_b32 s37, s3, 10
	s_add_u32 s40, s14, 0x10000000
	s_addc_u32 s41, s15, 0
	s_mul_i32 s15, s30, 0x580000
	s_mul_hi_u32 s14, s30, 0x580000
	s_add_u32 s10, s10, s15
	s_addc_u32 s11, s11, s14
	s_add_u32 s42, s10, 0x4900000
	s_addc_u32 s43, s11, 0
	s_mul_i32 s11, s88, 0x160000
	v_ashrrev_i16_sdwa v2, v7, sext(v2) dst_sel:DWORD dst_unused:UNUSED_PAD src0_sel:DWORD src1_sel:BYTE_0
	s_mul_hi_i32 s10, s88, 0x160000
	s_add_u32 s34, s42, s11
	v_bfe_i32 v20, v2, 0, 16
	v_and_b32_e32 v4, 24, v4
	v_and_b32_e32 v5, 4, v5
	s_addc_u32 s35, s43, s10
	s_add_i32 s44, s37, 0
	v_add_u32_e32 v2, v18, v20
	v_or3_b32 v4, v6, v5, v4
	s_add_i32 m0, s44, 0x10000
	v_add_lshl_u32 v196, v2, v3, 1
	v_lshrrev_b32_e32 v245, 4, v246
	v_mul_u32_u24_e32 v245, 0x16000, v245
	v_and_b32_e32 v247, 15, v246
	v_lshl_add_u32 v245, v247, 6, v245
	v_lshrrev_b32_e32 v247, 5, v2
	v_lshl_add_u32 v245, v247, 10, v245
	v_and_b32_e32 v247, 31, v2
	v_lshl_add_u32 v245, v247, 1, v245
	v_mov_b32_e32 v196, v245
	v_mul_u32_u24_e32 v3, 0xb00, v4
	global_load_lds_dwordx4 v194, s[34:35]
	s_add_i32 m0, s44, 0x12000
	v_add_lshl_u32 v198, v3, v2, 1
	s_add_u32 s10, s34, 0xb0000
	global_load_lds_dwordx4 v198, s[34:35]
	s_addc_u32 s11, s35, 0
	s_add_i32 m0, s44, 0x14000
	s_mul_i32 s15, s87, 0x160000
	global_load_lds_dwordx4 v194, s[10:11]
	s_add_i32 m0, s44, 0x16000
	s_mul_hi_i32 s14, s87, 0x160000
	global_load_lds_dwordx4 v198, s[10:11]
	s_add_u32 s10, s40, s15
	s_addc_u32 s11, s41, s14
	s_add_i32 s45, s44, 0x2000
	s_mov_b32 m0, s44
	s_add_u32 s14, s10, 0xb0000
	global_load_lds_dwordx4 v14, s[10:11]
	s_mov_b32 m0, s45
	s_addc_u32 s15, s11, 0
	s_add_i32 s46, s44, 0x4000
	global_load_lds_dwordx4 v196, s[10:11]
	s_mov_b32 m0, s46
	s_add_i32 s47, s44, 0x6000
	global_load_lds_dwordx4 v14, s[14:15]
	s_mov_b32 m0, s47
	v_mov_b32_e32 v195, v1
	global_load_lds_dwordx4 v196, s[14:15]
	v_mov_b32_e32 v199, v1
	v_mov_b32_e32 v15, v1
	v_mov_b32_e32 v197, v1
	s_cmp_eq_u32 s2, 1
	v_lshl_add_u64 v[8:9], s[34:35], 0, v[194:195]
	v_lshl_add_u64 v[6:7], s[34:35], 0, v[198:199]
	v_lshl_add_u64 v[2:3], s[10:11], 0, v[14:15]
	s_cselect_b64 s[14:15], -1, 0
	s_cmp_lg_u32 s2, 1
	v_lshl_add_u64 v[4:5], s[10:11], 0, v[196:197]
	s_cbranch_scc1 .LBB0_1229
	s_barrier
; __device__ __forceinline__ int opaque_tid(int wave_s) { int l; asm volatile("v_mbcnt_lo_u32_b32 %0, -1, 0\n\tv_mbcnt_hi_u32_b32 %0, -1, %0" : "=v"(l)); return (wave_s << 6) | l; }
; #define PG8_STAGE(bufoff, gbase, voff) do { _Pragma("unroll") for (int _i = 0; _i < 2; ++_i) \
;         __builtin_amdgcn_global_load_lds((const unsigned*)((const char*)(gbase) + (voff)[_i]), (PG8_LAS unsigned*)(lds + (bufoff) + ldsw + _i * 8192), 16, 0, 0); } while (0)
; #define PG8_WAIT_V(n) asm volatile("s_waitcnt vmcnt(" #n ")" ::: "memory")
; #define PG8_BAR __builtin_amdgcn_s_barrier()
; template <class Epi, class Sched, bool ALIGN_EPI = false, bool SP2 = false>
; __device__ __forceinline__ void gemm_phase(PG8_LAS unsigned char* lds, const Gemm g, const Sched& S, const Epi& E, const int wave_s) {
;     ...
;         PG8_STAGE(PG8_SB(1, 0), cB + kstep, voffB); PG8_STAGE(PG8_SA(1, 0), cA + kstep, voffA); PG8_STAGE(PG8_SB(1, 1), cB + hstepB + kstep, voffB);
;         PG8_WAIT_V(6); PG8_BAR;
;     ...
;         const bool has_next = S.next(ui + 1, nxt);
;         const char* nA = has_next ? (const char*)g.A + (size_t)nxt.pm * tstepA : cA; const char* nB = has_next ? (const char*)g.Bt + (size_t)nxt.pn * tstepB : cB;
;         for (int t = 0; t < nt; t += 2) {
;             if constexpr (Epi::KHOOK) { if (t == 6 || t == 12) { const int l3_ = opaque_tid(wave_s) & 63; E.khook(acc, t, wr, l3_ & 15, ui & 1, lds); } }
;             const bool last = (t == nt - 2);
;             const char* a1 = cA + (size_t)(t + 1) * kstep;
;             const char* a2 = last ? nA : cA + (size_t)(t + 2) * kstep; const char* b2 = last ? nB : cB + (size_t)(t + 2) * kstep;
;             const char* a3 = a2 + kstep; const char* b3 = b2 + kstep;
.LBB0_1229:
	s_and_b64 s[4:5], s[4:5], exec
	s_cselect_b32 s52, 3, s66
	s_mul_i32 s23, s52, 0x60000
	s_lshl_b64 s[4:5], s[52:53], 22
	s_mul_hi_u32 s22, s52, 0x60000
	s_add_u32 s18, s18, s23
	s_addc_u32 s19, s19, s22
	s_add_u32 s48, s18, 0x6001000
	s_addc_u32 s49, s19, 0
	s_add_u32 s4, s16, s4
	s_addc_u32 s5, s17, s5
	s_add_u32 s16, s4, 0x3d000000
	v_and_b32_e32 v21, 48, v17
	v_lshlrev_b32_e32 v22, 6, v17
	s_movk_i32 s4, 0x3c0
	v_lshlrev_b32_e32 v17, 2, v17
	s_addc_u32 s17, s5, 0
	s_lshl_b32 s50, s2, 6
	s_lshl_b32 s2, s2, 13
	v_and_or_b32 v21, v22, s4, v21
	v_and_b32_e32 v17, 32, v17
	s_load_dwordx2 s[4:5], s[0:1], 0x28
	v_bitop3_b32 v22, v21, s2, v17 bitop3:0xde
	s_lshl_b32 s2, s3, 5
	s_and_b32 s51, s2, 0x60
	s_lshl_b32 s2, s51, 7
	s_lshl_b32 s52, s52, 10
	v_bitop3_b32 v17, s2, v21, v17 bitop3:0xf6
	s_lshl_b64 s[2:3], s[52:53], 2
	s_waitcnt lgkmcnt(0)
	s_add_u32 s18, s4, s2
	s_addc_u32 s19, s5, s3
	s_ashr_i32 s52, s36, 31
	s_add_u32 s20, s20, 0x8000000
	s_addc_u32 s21, s21, 0
	s_add_u32 s22, s8, 0x8000000
	s_addc_u32 s23, s9, 0
	v_readlane_b32 s2, v255, 23
	s_add_u32 s2, s6, s2
	v_readlane_b32 s3, v255, 22
	s_addc_u32 s3, s7, s3
	s_add_u32 s67, s2, 0x6005000
	s_addc_u32 s73, s3, 0
	s_add_i32 m0, s44, 0x18000
	v_lshl_add_u64 v[8:9], v[8:9], 0, s[58:59]
	s_waitcnt vmcnt(2)
	s_barrier
	global_load_lds_dwordx4 v[8:9], off
	v_lshl_add_u64 v[6:7], v[6:7], 0, s[58:59]
	s_add_i32 m0, s44, 0x1a000
	s_add_i32 s80, s44, 0x8000
	s_add_i32 s81, s44, 0xa000
	global_load_lds_dwordx4 v[6:7], off
	v_lshl_add_u64 v[2:3], v[2:3], 0, v[248:249]
	s_mov_b32 m0, s80
	s_add_u32 s2, s34, 0xb0080
	global_load_lds_dwordx4 v[2:3], off
	v_lshl_add_u64 v[2:3], v[4:5], 0, v[248:249]
	s_mov_b32 m0, s81
	s_addc_u32 s3, s35, 0
	global_load_lds_dwordx4 v[2:3], off
	s_add_i32 m0, s44, 0x1c000
	v_lshl_add_u64 v[2:3], s[2:3], 0, v[194:195]
	global_load_lds_dwordx4 v[2:3], off
	v_lshl_add_u64 v[2:3], s[2:3], 0, v[198:199]
	s_add_i32 m0, s44, 0x1e000
	s_movk_i32 s5, 0xb00
	global_load_lds_dwordx4 v[2:3], off
	v_lshrrev_b32_e32 v2, 1, v0
	v_mul_lo_u32 v0, v19, s5
	s_mov_b32 s4, 0xb000
	v_mad_u64_u32 v[2:3], s[2:3], v2, s4, v[0:1]
	v_or_b32_e32 v0, v2, v18
	v_add_lshl_u32 v0, v0, v20, 1
	s_mov_b64 s[6:7], 0xb0080
	v_lshl_add_u64 v[200:201], v[0:1], 0, s[6:7]
	v_lshrrev_b32_e32 v2, 1, v10
	v_mul_lo_u32 v0, v12, s5
	v_mad_u64_u32 v[2:3], s[2:3], v2, s4, v[0:1]
	s_waitcnt vmcnt(6)
	s_cmpk_lt_u32 s24, 0x100
	v_or_b32_e32 v0, v2, v11
	s_cselect_b64 s[24:25], -1, 0
	s_cmp_lg_u64 s[12:13], 0
	v_add_lshl_u32 v0, v0, v13, 1
	s_cselect_b64 s[26:27], -1, 0
	v_lshl_add_u64 v[202:203], v[0:1], 0, s[6:7]
	s_mov_b64 s[6:7], 0xb0800
	v_lshl_add_u64 v[202:203], v[14:15], 0, s[6:7]
	v_lshl_add_u64 v[200:201], v[196:197], 0, s[6:7]
	s_mov_b32 s82, 0
	v_add_u32_e32 v216, 0, v22
	s_barrier
	s_branch .LBB0_1232

; __device__ __forceinline__ int opaque_tid(int wave_s) { int l; asm volatile("v_mbcnt_lo_u32_b32 %0, -1, 0\n\tv_mbcnt_hi_u32_b32 %0, -1, %0" : "=v"(l)); return (wave_s << 6) | l; }
; #define PG8_STAGE(bufoff, gbase, voff) do { _Pragma("unroll") for (int _i = 0; _i < 2; ++_i) \
;         __builtin_amdgcn_global_load_lds((const unsigned*)((const char*)(gbase) + (voff)[_i]), (PG8_LAS unsigned*)(lds + (bufoff) + ldsw + _i * 8192), 16, 0, 0); } while (0)
; #define PG8_WAIT_V(n) asm volatile("s_waitcnt vmcnt(" #n ")" ::: "memory")
; template <class Epi, class Sched, bool ALIGN_EPI = false, bool SP2 = false>
; __device__ __forceinline__ void gemm_phase(PG8_LAS unsigned char* lds, const Gemm g, const Sched& S, const Epi& E, const int wave_s) {
;     ...
;         for (int t = 0; t < nt; t += 2) {
;             if constexpr (Epi::KHOOK) { if (t == 6 || t == 12) { const int l3_ = opaque_tid(wave_s) & 63; E.khook(acc, t, wr, l3_ & 15, ui & 1, lds); } }
;             const bool last = (t == nt - 2);
;             const char* a1 = cA + (size_t)(t + 1) * kstep;
;             const char* a2 = last ? nA : cA + (size_t)(t + 2) * kstep; const char* b2 = last ? nB : cB + (size_t)(t + 2) * kstep;
;             const char* a3 = a2 + kstep; const char* b3 = b2 + kstep;
;             if (last && has_next) S.a_ready(nxt);
;             if constexpr (SP2) {
;             PG8_LDB(B0, 0, 0); PG8_LDB(B1, 0, 1); PG8_SCHED; PG8_LDA(At, 0, 0); PG8_STAGE(PG8_SA(1, 1), a1 + hstepA, voffA);
;             PG8_WAIT_V(8); PG8_WAIT_L(0); PG8_BAR; PG8_MMA(0, 0, At, B0); PG8_MMA(0, 1, At, B1); PG8_BAR; PG8_SCHED;
;             PG8_LDA(At, 0, 1); PG8_STAGE(PG8_SB(0, 0), b2, voffB); PG8_STAGE(PG8_SB(0, 1), b2 + hstepB, voffB); PG8_STAGE(PG8_SA(0, 0), a2, voffA);
;             PG8_WAIT_V(8); PG8_WAIT_L(0); PG8_BAR; PG8_MMA(1, 0, At, B0); PG8_MMA(1, 1, At, B1); PG8_BAR; PG8_SCHED;
;             PG8_LDB(B0, 1, 0); PG8_LDB(B1, 1, 1); PG8_SCHED; PG8_LDA(At, 1, 0); PG8_STAGE(PG8_SA(0, 1), a2 + hstepA, voffA);
;             PG8_WAIT_V(8); PG8_WAIT_L(0); PG8_BAR; PG8_MMA(0, 0, At, B0); PG8_MMA(0, 1, At, B1); PG8_BAR; PG8_SCHED;
;             PG8_LDA(At, 1, 1); PG8_STAGE(PG8_SB(1, 0), b3, voffB); PG8_STAGE(PG8_SB(1, 1), b3 + hstepB, voffB); PG8_STAGE(PG8_SA(1, 0), a3, voffA);
;             PG8_WAIT_V(8); PG8_WAIT_L(0); PG8_BAR; PG8_MMA(1, 0, At, B0); PG8_MMA(1, 1, At, B1); PG8_BAR; PG8_SCHED;
.LBB0_1243:
	s_add_u32 s8, s10, 0x1000
	s_addc_u32 s9, s11, 0
	s_add_i32 s55, 0, 0x10000
	s_cmp_eq_u32 s54, 40
	s_cselect_b32 s35, s29, s9
	s_cselect_b32 s34, s28, s8
	v_add_u32_e32 v0, s55, v17
	s_cselect_b32 s5, s31, s3
	s_cselect_b32 s4, s30, s2
	s_add_i32 s56, 0, 0x14000
	ds_read_b128 v[62:65], v0
	ds_read_b128 v[66:69], v0 offset:1024
	ds_read_b128 v[70:73], v0 offset:2048
	ds_read_b128 v[74:77], v0 offset:3072
	v_add_u32_e32 v0, s56, v17
	ds_read_b128 v[150:153], v0
	ds_read_b128 v[154:157], v0 offset:1024
	ds_read_b128 v[158:161], v0 offset:2048
	ds_read_b128 v[162:165], v0 offset:3072
	v_lshl_add_u64 v[208:209], s[10:11], 0, v[202:203]
	s_add_i32 m0, s44, 0xc000
	ds_read_b128 v[166:169], v216
	ds_read_b128 v[170:173], v216 offset:1024
	ds_read_b128 v[174:177], v216 offset:2048
	ds_read_b128 v[178:181], v216 offset:3072
	ds_read_b128 v[182:185], v216 offset:4096
	ds_read_b128 v[186:189], v216 offset:5120
	ds_read_b128 v[190:193], v216 offset:6144
	ds_read_b128 v[204:207], v216 offset:7168
	global_load_lds_dwordx4 v[208:209], off
	v_lshl_add_u64 v[208:209], s[10:11], 0, v[200:201]
	s_add_i32 m0, s44, 0xe000
	s_nop 0
	global_load_lds_dwordx4 v[208:209], off
	s_waitcnt vmcnt(8)
	s_waitcnt lgkmcnt(0)
	s_barrier
	s_setprio 1
	s_waitcnt lgkmcnt(0)
	v_mfma_f32_16x16x32_bf16 v[146:149], v[62:65], v[166:169], v[146:149]
	v_mfma_f32_16x16x32_bf16 v[142:145], v[70:73], v[166:169], v[142:145]
	v_mfma_f32_16x16x32_bf16 v[130:133], v[62:65], v[174:177], v[130:133]
	v_mfma_f32_16x16x32_bf16 v[126:129], v[70:73], v[174:177], v[126:129]
	v_mfma_f32_16x16x32_bf16 v[114:117], v[62:65], v[182:185], v[114:117]
	v_mfma_f32_16x16x32_bf16 v[110:113], v[70:73], v[182:185], v[110:113]
	v_mfma_f32_16x16x32_bf16 v[98:101], v[62:65], v[190:193], v[98:101]
	v_mfma_f32_16x16x32_bf16 v[94:97], v[70:73], v[190:193], v[94:97]
	v_mfma_f32_16x16x32_bf16 v[146:149], v[66:69], v[170:173], v[146:149]
	v_mfma_f32_16x16x32_bf16 v[142:145], v[74:77], v[170:173], v[142:145]
	v_mfma_f32_16x16x32_bf16 v[130:133], v[66:69], v[178:181], v[130:133]
	v_mfma_f32_16x16x32_bf16 v[126:129], v[74:77], v[178:181], v[126:129]
	v_mfma_f32_16x16x32_bf16 v[114:117], v[66:69], v[186:189], v[114:117]
	v_mfma_f32_16x16x32_bf16 v[110:113], v[74:77], v[186:189], v[110:113]
	v_mfma_f32_16x16x32_bf16 v[98:101], v[66:69], v[204:207], v[98:101]
	v_mfma_f32_16x16x32_bf16 v[94:97], v[74:77], v[204:207], v[94:97]
	s_setprio 0
	s_setprio 1
	v_mfma_f32_16x16x32_bf16 v[138:141], v[150:153], v[166:169], v[138:141]
	v_mfma_f32_16x16x32_bf16 v[134:137], v[158:161], v[166:169], v[134:137]
	v_mfma_f32_16x16x32_bf16 v[122:125], v[150:153], v[174:177], v[122:125]
	v_mfma_f32_16x16x32_bf16 v[118:121], v[158:161], v[174:177], v[118:121]
	v_mfma_f32_16x16x32_bf16 v[106:109], v[150:153], v[182:185], v[106:109]
	v_mfma_f32_16x16x32_bf16 v[102:105], v[158:161], v[182:185], v[102:105]
	v_mfma_f32_16x16x32_bf16 v[90:93], v[150:153], v[190:193], v[90:93]
	v_mfma_f32_16x16x32_bf16 v[86:89], v[158:161], v[190:193], v[86:89]
	v_mfma_f32_16x16x32_bf16 v[138:141], v[154:157], v[170:173], v[138:141]
	v_mfma_f32_16x16x32_bf16 v[134:137], v[162:165], v[170:173], v[134:137]
	v_mfma_f32_16x16x32_bf16 v[122:125], v[154:157], v[178:181], v[122:125]
	v_mfma_f32_16x16x32_bf16 v[118:121], v[162:165], v[178:181], v[118:121]
	v_mfma_f32_16x16x32_bf16 v[106:109], v[154:157], v[186:189], v[106:109]
	v_mfma_f32_16x16x32_bf16 v[102:105], v[162:165], v[186:189], v[102:105]
	v_mfma_f32_16x16x32_bf16 v[90:93], v[154:157], v[204:207], v[90:93]
	v_mfma_f32_16x16x32_bf16 v[86:89], v[162:165], v[204:207], v[86:89]
	s_setprio 0
	s_barrier
	s_add_i32 s10, s55, s37
	v_lshl_add_u64 v[208:209], s[4:5], 0, v[194:195]
	s_mov_b32 m0, s10
	ds_read_b128 v[166:169], v216 offset:16384
	ds_read_b128 v[170:173], v216 offset:17408
	ds_read_b128 v[174:177], v216 offset:18432
	ds_read_b128 v[178:181], v216 offset:19456
	ds_read_b128 v[182:185], v216 offset:20480
	ds_read_b128 v[186:189], v216 offset:21504
	ds_read_b128 v[190:193], v216 offset:22528
	ds_read_b128 v[204:207], v216 offset:23552
	global_load_lds_dwordx4 v[208:209], off
	s_add_i32 m0, s10, 0x2000
	s_add_u32 s10, s4, 0xb0000
	v_lshl_add_u64 v[210:211], s[4:5], 0, v[198:199]
	s_addc_u32 s11, s5, 0
	s_add_i32 s55, s56, s37
	global_load_lds_dwordx4 v[210:211], off
	v_lshl_add_u64 v[212:213], s[10:11], 0, v[194:195]
	s_mov_b32 m0, s55
	v_lshl_add_u64 v[214:215], s[34:35], 0, v[196:197]
	global_load_lds_dwordx4 v[212:213], off
	v_lshl_add_u64 v[212:213], s[10:11], 0, v[198:199]
	s_add_i32 m0, s55, 0x2000
	s_nop 0
	global_load_lds_dwordx4 v[212:213], off
	v_lshl_add_u64 v[212:213], s[34:35], 0, v[14:15]
	s_mov_b32 m0, s44
	s_nop 0
	global_load_lds_dwordx4 v[212:213], off
	s_mov_b32 m0, s45
	s_nop 0
	global_load_lds_dwordx4 v[214:215], off
	s_waitcnt vmcnt(8)
	s_waitcnt lgkmcnt(0)
	s_barrier
; #define PG8_STAGE(bufoff, gbase, voff) do { _Pragma("unroll") for (int _i = 0; _i < 2; ++_i) \
;         __builtin_amdgcn_global_load_lds((const unsigned*)((const char*)(gbase) + (voff)[_i]), (PG8_LAS unsigned*)(lds + (bufoff) + ldsw + _i * 8192), 16, 0, 0); } while (0)
; #define PG8_LDA(dst, b, h) do { _Pragma("unroll") for (int m = 0; m < 4; ++m) _Pragma("unroll") for (int k = 0; k < 2; ++k) dst[m][k] = *(const PG8_LAS bf16x8*)(lds + PG8_SA(b, h) + aoff + m * 2048 + k * 1024); } while (0)
; #define PG8_LDB(dst, b, h) do { _Pragma("unroll") for (int n = 0; n < 2; ++n) _Pragma("unroll") for (int k = 0; k < 2; ++k) dst[n][k] = *(const PG8_LAS bf16x8*)(lds + PG8_SB(b, h) + boff + n * 2048 + k * 1024); } while (0)
; #define PG8_MMA(ai, bj, At, Bt) do { __builtin_amdgcn_s_setprio(1); _Pragma("unroll") for (int m = 0; m < 4; ++m) _Pragma("unroll") for (int n = 0; n < 2; ++n) _Pragma("unroll") for (int k = 0; k < 2; ++k) \
;         acc[ai][bj][m][n] = __builtin_amdgcn_mfma_f32_16x16x32_bf16(Bt[n][k], At[m][k], acc[ai][bj][m][n], 0, 0, 0); __builtin_amdgcn_s_setprio(0); } while (0)
; #define PG8_WAIT_V(n) asm volatile("s_waitcnt vmcnt(" #n ")" ::: "memory")
; #define PG8_WAIT_L(n) asm volatile("s_waitcnt lgkmcnt(" #n ")" ::: "memory")
; #define PG8_BAR __builtin_amdgcn_s_barrier()
; #define PG8_SCHED __builtin_amdgcn_sched_barrier(0)
; template <class Epi, class Sched, bool ALIGN_EPI = false, bool SP2 = false>
; __device__ __forceinline__ void gemm_phase(PG8_LAS unsigned char* lds, const Gemm g, const Sched& S, const Epi& E, const int wave_s) {
;     ...
;             PG8_WAIT_V(8); PG8_WAIT_L(0); PG8_BAR; PG8_MMA(1, 0, At, B0); PG8_MMA(1, 1, At, B1); PG8_BAR; PG8_SCHED;
;             PG8_LDB(B0, 1, 0); PG8_LDB(B1, 1, 1); PG8_SCHED; PG8_LDA(At, 1, 0); PG8_STAGE(PG8_SA(0, 1), a2 + hstepA, voffA);
;             PG8_WAIT_V(8); PG8_WAIT_L(0); PG8_BAR; PG8_MMA(0, 0, At, B0); PG8_MMA(0, 1, At, B1); PG8_BAR; PG8_SCHED;
;             PG8_LDA(At, 1, 1); PG8_STAGE(PG8_SB(1, 0), b3, voffB); PG8_STAGE(PG8_SB(1, 1), b3 + hstepB, voffB); PG8_STAGE(PG8_SA(1, 0), a3, voffA);
;             PG8_WAIT_V(8); PG8_WAIT_L(0); PG8_BAR; PG8_MMA(1, 0, At, B0); PG8_MMA(1, 1, At, B1); PG8_BAR; PG8_SCHED;
	s_setprio 1
	s_waitcnt lgkmcnt(0)
	v_mfma_f32_16x16x32_bf16 v[82:85], v[62:65], v[166:169], v[82:85]
	v_mfma_f32_16x16x32_bf16 v[78:81], v[70:73], v[166:169], v[78:81]
	v_mfma_f32_16x16x32_bf16 v[50:53], v[62:65], v[174:177], v[50:53]
	v_mfma_f32_16x16x32_bf16 v[46:49], v[70:73], v[174:177], v[46:49]
	v_mfma_f32_16x16x32_bf16 v[34:37], v[62:65], v[182:185], v[34:37]
	v_mfma_f32_16x16x32_bf16 v[30:33], v[70:73], v[182:185], v[30:33]
	v_mfma_f32_16x16x32_bf16 v[18:21], v[62:65], v[190:193], v[18:21]
	v_mfma_f32_16x16x32_bf16 v[10:13], v[70:73], v[190:193], v[10:13]
	v_mfma_f32_16x16x32_bf16 v[82:85], v[66:69], v[170:173], v[82:85]
	v_mfma_f32_16x16x32_bf16 v[78:81], v[74:77], v[170:173], v[78:81]
	v_mfma_f32_16x16x32_bf16 v[50:53], v[66:69], v[178:181], v[50:53]
	v_mfma_f32_16x16x32_bf16 v[46:49], v[74:77], v[178:181], v[46:49]
	v_mfma_f32_16x16x32_bf16 v[34:37], v[66:69], v[186:189], v[34:37]
	v_mfma_f32_16x16x32_bf16 v[30:33], v[74:77], v[186:189], v[30:33]
	v_mfma_f32_16x16x32_bf16 v[18:21], v[66:69], v[204:207], v[18:21]
	v_mfma_f32_16x16x32_bf16 v[10:13], v[74:77], v[204:207], v[10:13]
	s_setprio 0
	s_setprio 1
	v_mfma_f32_16x16x32_bf16 v[58:61], v[150:153], v[166:169], v[58:61]
	v_mfma_f32_16x16x32_bf16 v[54:57], v[158:161], v[166:169], v[54:57]
	v_mfma_f32_16x16x32_bf16 v[42:45], v[150:153], v[174:177], v[42:45]
	v_mfma_f32_16x16x32_bf16 v[38:41], v[158:161], v[174:177], v[38:41]
	v_mfma_f32_16x16x32_bf16 v[26:29], v[150:153], v[182:185], v[26:29]
	v_mfma_f32_16x16x32_bf16 v[22:25], v[158:161], v[182:185], v[22:25]
	v_mfma_f32_16x16x32_bf16 v[6:9], v[150:153], v[190:193], v[6:9]
	v_mfma_f32_16x16x32_bf16 v[2:5], v[158:161], v[190:193], v[2:5]
	v_mfma_f32_16x16x32_bf16 v[58:61], v[154:157], v[170:173], v[58:61]
	v_mfma_f32_16x16x32_bf16 v[54:57], v[162:165], v[170:173], v[54:57]
	v_mfma_f32_16x16x32_bf16 v[42:45], v[154:157], v[178:181], v[42:45]
	v_mfma_f32_16x16x32_bf16 v[38:41], v[162:165], v[178:181], v[38:41]
	v_mfma_f32_16x16x32_bf16 v[26:29], v[154:157], v[186:189], v[26:29]
	v_mfma_f32_16x16x32_bf16 v[22:25], v[162:165], v[186:189], v[22:25]
	v_mfma_f32_16x16x32_bf16 v[6:9], v[154:157], v[204:207], v[6:9]
	v_mfma_f32_16x16x32_bf16 v[2:5], v[162:165], v[204:207], v[2:5]
	s_setprio 0
	s_barrier
	s_add_i32 s55, 0, 0x18000
	v_add_u32_e32 v0, s55, v17
	s_add_i32 s56, 0, 0x1c000
	ds_read_b128 v[62:65], v0
	ds_read_b128 v[66:69], v0 offset:1024
	ds_read_b128 v[70:73], v0 offset:2048
	ds_read_b128 v[74:77], v0 offset:3072
	v_add_u32_e32 v0, s56, v17
	ds_read_b128 v[150:153], v0
	ds_read_b128 v[154:157], v0 offset:1024
	ds_read_b128 v[158:161], v0 offset:2048
	ds_read_b128 v[162:165], v0 offset:3072
	s_add_u32 s10, s34, 0xb0000
	s_addc_u32 s11, s35, 0
	s_mov_b32 m0, s46
	v_lshl_add_u64 v[218:219], s[10:11], 0, v[14:15]
	ds_read_b128 v[166:169], v216 offset:32768
	ds_read_b128 v[170:173], v216 offset:33792
	ds_read_b128 v[174:177], v216 offset:34816
	ds_read_b128 v[178:181], v216 offset:35840
	ds_read_b128 v[182:185], v216 offset:36864
	ds_read_b128 v[186:189], v216 offset:37888
	ds_read_b128 v[190:193], v216 offset:38912
	ds_read_b128 v[204:207], v216 offset:39936
	global_load_lds_dwordx4 v[218:219], off
	v_lshl_add_u64 v[218:219], s[10:11], 0, v[196:197]
	s_mov_b32 m0, s47
	s_nop 0
	global_load_lds_dwordx4 v[218:219], off
	s_waitcnt vmcnt(8)
	s_waitcnt lgkmcnt(0)
	s_barrier
	s_setprio 1
	s_waitcnt lgkmcnt(0)
	v_mfma_f32_16x16x32_bf16 v[146:149], v[62:65], v[166:169], v[146:149]
	v_mfma_f32_16x16x32_bf16 v[142:145], v[70:73], v[166:169], v[142:145]
	v_mfma_f32_16x16x32_bf16 v[130:133], v[62:65], v[174:177], v[130:133]
	v_mfma_f32_16x16x32_bf16 v[126:129], v[70:73], v[174:177], v[126:129]
	v_mfma_f32_16x16x32_bf16 v[114:117], v[62:65], v[182:185], v[114:117]
	v_mfma_f32_16x16x32_bf16 v[110:113], v[70:73], v[182:185], v[110:113]
	v_mfma_f32_16x16x32_bf16 v[98:101], v[62:65], v[190:193], v[98:101]
	v_mfma_f32_16x16x32_bf16 v[94:97], v[70:73], v[190:193], v[94:97]
	v_mfma_f32_16x16x32_bf16 v[146:149], v[66:69], v[170:173], v[146:149]
	v_mfma_f32_16x16x32_bf16 v[142:145], v[74:77], v[170:173], v[142:145]
	v_mfma_f32_16x16x32_bf16 v[130:133], v[66:69], v[178:181], v[130:133]
	v_mfma_f32_16x16x32_bf16 v[126:129], v[74:77], v[178:181], v[126:129]
	v_mfma_f32_16x16x32_bf16 v[114:117], v[66:69], v[186:189], v[114:117]
	v_mfma_f32_16x16x32_bf16 v[110:113], v[74:77], v[186:189], v[110:113]
	v_mfma_f32_16x16x32_bf16 v[98:101], v[66:69], v[204:207], v[98:101]
	v_mfma_f32_16x16x32_bf16 v[94:97], v[74:77], v[204:207], v[94:97]
	s_setprio 0
	s_setprio 1
	v_mfma_f32_16x16x32_bf16 v[138:141], v[150:153], v[166:169], v[138:141]
	v_mfma_f32_16x16x32_bf16 v[134:137], v[158:161], v[166:169], v[134:137]
	v_mfma_f32_16x16x32_bf16 v[122:125], v[150:153], v[174:177], v[122:125]
	v_mfma_f32_16x16x32_bf16 v[118:121], v[158:161], v[174:177], v[118:121]
	v_mfma_f32_16x16x32_bf16 v[106:109], v[150:153], v[182:185], v[106:109]
	v_mfma_f32_16x16x32_bf16 v[102:105], v[158:161], v[182:185], v[102:105]
	v_mfma_f32_16x16x32_bf16 v[90:93], v[150:153], v[190:193], v[90:93]
	v_mfma_f32_16x16x32_bf16 v[86:89], v[158:161], v[190:193], v[86:89]
	v_mfma_f32_16x16x32_bf16 v[138:141], v[154:157], v[170:173], v[138:141]
	v_mfma_f32_16x16x32_bf16 v[134:137], v[162:165], v[170:173], v[134:137]
	v_mfma_f32_16x16x32_bf16 v[122:125], v[154:157], v[178:181], v[122:125]
	v_mfma_f32_16x16x32_bf16 v[118:121], v[162:165], v[178:181], v[118:121]
	v_mfma_f32_16x16x32_bf16 v[106:109], v[154:157], v[186:189], v[106:109]
	v_mfma_f32_16x16x32_bf16 v[102:105], v[162:165], v[186:189], v[102:105]
	v_mfma_f32_16x16x32_bf16 v[90:93], v[154:157], v[204:207], v[90:93]
	v_mfma_f32_16x16x32_bf16 v[86:89], v[162:165], v[204:207], v[86:89]
	s_setprio 0
	s_barrier
; __device__ __forceinline__ int opaque_tid(int wave_s) { int l; asm volatile("v_mbcnt_lo_u32_b32 %0, -1, 0\n\tv_mbcnt_hi_u32_b32 %0, -1, %0" : "=v"(l)); return (wave_s << 6) | l; }
; #define PG8_STAGE(bufoff, gbase, voff) do { _Pragma("unroll") for (int _i = 0; _i < 2; ++_i) \
;         __builtin_amdgcn_global_load_lds((const unsigned*)((const char*)(gbase) + (voff)[_i]), (PG8_LAS unsigned*)(lds + (bufoff) + ldsw + _i * 8192), 16, 0, 0); } while (0)
; #define PG8_LDA(dst, b, h) do { _Pragma("unroll") for (int m = 0; m < 4; ++m) _Pragma("unroll") for (int k = 0; k < 2; ++k) dst[m][k] = *(const PG8_LAS bf16x8*)(lds + PG8_SA(b, h) + aoff + m * 2048 + k * 1024); } while (0)
; #define PG8_MMA(ai, bj, At, Bt) do { __builtin_amdgcn_s_setprio(1); _Pragma("unroll") for (int m = 0; m < 4; ++m) _Pragma("unroll") for (int n = 0; n < 2; ++n) _Pragma("unroll") for (int k = 0; k < 2; ++k) \
;         acc[ai][bj][m][n] = __builtin_amdgcn_mfma_f32_16x16x32_bf16(Bt[n][k], At[m][k], acc[ai][bj][m][n], 0, 0, 0); __builtin_amdgcn_s_setprio(0); } while (0)
; #define PG8_WAIT_V(n) asm volatile("s_waitcnt vmcnt(" #n ")" ::: "memory")
; #define PG8_WAIT_L(n) asm volatile("s_waitcnt lgkmcnt(" #n ")" ::: "memory")
; #define PG8_BAR __builtin_amdgcn_s_barrier()
; #define PG8_SCHED __builtin_amdgcn_sched_barrier(0)
; template <class Epi, class Sched, bool ALIGN_EPI = false, bool SP2 = false>
; __device__ __forceinline__ void gemm_phase(PG8_LAS unsigned char* lds, const Gemm g, const Sched& S, const Epi& E, const int wave_s) {
;     ...
;         for (int t = 0; t < nt; t += 2) {
;             if constexpr (Epi::KHOOK) { if (t == 6 || t == 12) { const int l3_ = opaque_tid(wave_s) & 63; E.khook(acc, t, wr, l3_ & 15, ui & 1, lds); } }
;             const bool last = (t == nt - 2);
;             const char* a1 = cA + (size_t)(t + 1) * kstep;
;             const char* a2 = last ? nA : cA + (size_t)(t + 2) * kstep; const char* b2 = last ? nB : cB + (size_t)(t + 2) * kstep;
;     ...
;             PG8_WAIT_V(8); PG8_WAIT_L(0); PG8_BAR; PG8_MMA(0, 0, At, B0); PG8_MMA(0, 1, At, B1); PG8_BAR; PG8_SCHED;
;             PG8_LDA(At, 1, 1); PG8_STAGE(PG8_SB(1, 0), b3, voffB); PG8_STAGE(PG8_SB(1, 1), b3 + hstepB, voffB); PG8_STAGE(PG8_SA(1, 0), a3, voffA);
;             PG8_WAIT_V(8); PG8_WAIT_L(0); PG8_BAR; PG8_MMA(1, 0, At, B0); PG8_MMA(1, 1, At, B1); PG8_BAR; PG8_SCHED;
	s_add_i32 s10, s55, s37
	v_lshl_add_u64 v[208:209], v[208:209], 0, s[58:59]
	s_mov_b32 m0, s10
	ds_read_b128 v[166:169], v216 offset:49152
	ds_read_b128 v[170:173], v216 offset:50176
	ds_read_b128 v[174:177], v216 offset:51200
	ds_read_b128 v[178:181], v216 offset:52224
	ds_read_b128 v[182:185], v216 offset:53248
	ds_read_b128 v[186:189], v216 offset:54272
	ds_read_b128 v[190:193], v216 offset:55296
	ds_read_b128 v[204:207], v216 offset:56320
	global_load_lds_dwordx4 v[208:209], off
	s_add_i32 m0, s10, 0x2000
	s_add_u32 s4, s4, 0xb0080
	v_lshl_add_u64 v[208:209], v[210:211], 0, s[58:59]
	s_addc_u32 s5, s5, 0
	s_add_i32 s10, s56, s37
	global_load_lds_dwordx4 v[208:209], off
	v_lshl_add_u64 v[208:209], s[4:5], 0, v[194:195]
	s_mov_b32 m0, s10
	s_nop 0
	global_load_lds_dwordx4 v[208:209], off
	v_lshl_add_u64 v[208:209], s[4:5], 0, v[198:199]
	s_add_i32 m0, s10, 0x2000
	s_nop 0
	global_load_lds_dwordx4 v[208:209], off
	v_lshl_add_u64 v[208:209], v[212:213], 0, v[248:249]
	s_mov_b32 m0, s80
	s_nop 0
	global_load_lds_dwordx4 v[208:209], off
	v_lshl_add_u64 v[208:209], v[214:215], 0, v[248:249]
	s_mov_b32 m0, s81
	s_nop 0
	global_load_lds_dwordx4 v[208:209], off
	s_waitcnt vmcnt(8)
	s_waitcnt lgkmcnt(0)
	s_barrier
	s_setprio 1
	s_waitcnt lgkmcnt(0)
	v_mfma_f32_16x16x32_bf16 v[82:85], v[62:65], v[166:169], v[82:85]
	v_mfma_f32_16x16x32_bf16 v[78:81], v[70:73], v[166:169], v[78:81]
	v_mfma_f32_16x16x32_bf16 v[50:53], v[62:65], v[174:177], v[50:53]
	v_mfma_f32_16x16x32_bf16 v[46:49], v[70:73], v[174:177], v[46:49]
	v_mfma_f32_16x16x32_bf16 v[34:37], v[62:65], v[182:185], v[34:37]
	v_mfma_f32_16x16x32_bf16 v[30:33], v[70:73], v[182:185], v[30:33]
	v_mfma_f32_16x16x32_bf16 v[18:21], v[62:65], v[190:193], v[18:21]
	v_mfma_f32_16x16x32_bf16 v[10:13], v[70:73], v[190:193], v[10:13]
	v_mfma_f32_16x16x32_bf16 v[82:85], v[66:69], v[170:173], v[82:85]
	v_mfma_f32_16x16x32_bf16 v[78:81], v[74:77], v[170:173], v[78:81]
	v_mfma_f32_16x16x32_bf16 v[50:53], v[66:69], v[178:181], v[50:53]
	v_mfma_f32_16x16x32_bf16 v[46:49], v[74:77], v[178:181], v[46:49]
	v_mfma_f32_16x16x32_bf16 v[34:37], v[66:69], v[186:189], v[34:37]
	v_mfma_f32_16x16x32_bf16 v[30:33], v[74:77], v[186:189], v[30:33]
	v_mfma_f32_16x16x32_bf16 v[18:21], v[66:69], v[204:207], v[18:21]
	v_mfma_f32_16x16x32_bf16 v[10:13], v[74:77], v[204:207], v[10:13]
	s_setprio 0
	s_setprio 1
	v_mfma_f32_16x16x32_bf16 v[58:61], v[150:153], v[166:169], v[58:61]
	v_mfma_f32_16x16x32_bf16 v[54:57], v[158:161], v[166:169], v[54:57]
	v_mfma_f32_16x16x32_bf16 v[42:45], v[150:153], v[174:177], v[42:45]
	v_mfma_f32_16x16x32_bf16 v[38:41], v[158:161], v[174:177], v[38:41]
	v_mfma_f32_16x16x32_bf16 v[26:29], v[150:153], v[182:185], v[26:29]
	v_mfma_f32_16x16x32_bf16 v[22:25], v[158:161], v[182:185], v[22:25]
	v_mfma_f32_16x16x32_bf16 v[6:9], v[150:153], v[190:193], v[6:9]
	v_mfma_f32_16x16x32_bf16 v[2:5], v[158:161], v[190:193], v[2:5]
	v_mfma_f32_16x16x32_bf16 v[58:61], v[154:157], v[170:173], v[58:61]
	v_mfma_f32_16x16x32_bf16 v[54:57], v[162:165], v[170:173], v[54:57]
	v_mfma_f32_16x16x32_bf16 v[42:45], v[154:157], v[178:181], v[42:45]
	v_mfma_f32_16x16x32_bf16 v[38:41], v[162:165], v[178:181], v[38:41]
	v_mfma_f32_16x16x32_bf16 v[26:29], v[154:157], v[186:189], v[26:29]
	v_mfma_f32_16x16x32_bf16 v[22:25], v[162:165], v[186:189], v[22:25]
	v_mfma_f32_16x16x32_bf16 v[6:9], v[154:157], v[204:207], v[6:9]
	v_mfma_f32_16x16x32_bf16 v[2:5], v[162:165], v[204:207], v[2:5]
	s_setprio 0
	s_barrier
	s_add_i32 s54, s54, 2
	s_add_u32 s2, s2, 0x100
	s_addc_u32 s3, s3, 0
	s_cmp_gt_u32 s54, 41
	s_mov_b64 s[10:11], s[8:9]
	s_cbranch_scc0 .LBB0_1243
	s_and_b64 vcc, exec, s[24:25]
	s_cbranch_vccz .LBB0_1246
	s_barrier
